# scan: helper waves also stage (GDN operands) by LDS-DMA; VGPR staging copies removed
# speedup vs baseline: 1.0407x; 1.0052x over previous
.Lsc_top_vgpr:
	v_readlane_b32 s4, v251, 0
	s_and_b32 s0, s13, 1
	s_xor_b32 s0, s0, 1
	s_mul_i32 s0, s0, 0x9900
	s_sub_u32 s4, s4, 4
	s_lshl_b32 s5, s4, 10
	s_add_i32 s0, s0, s5
	s_add_i32 s0, s0, 0x5400
	v_add_u32_e32 v0, s57, v147
	s_add_i32 m0, s0, 0x0
	s_nop 0
	global_load_lds_dwordx4 v0, s[16:17]
	v_add_u32_e32 v6, s57, v146
	s_add_i32 m0, s0, 0x1000
	s_nop 0
	global_load_lds_dwordx4 v6, s[16:17]
	v_add_u32_e32 v0, s57, v145
	s_add_i32 m0, s0, 0x2000
	s_nop 0
	global_load_lds_dwordx4 v0, s[16:17]
	v_add_u32_e32 v6, s57, v144
	s_add_i32 m0, s0, 0x3000
	s_nop 0
	global_load_lds_dwordx4 v6, s[16:17]
	s_cmp_gt_u32 s4, 1
	s_cbranch_scc1 .LBB0_1234
	v_add_u32_e32 v0, s57, v143
	s_add_i32 m0, s0, 0x4000
	s_cmp_eq_u32 s4, 0
	s_cbranch_scc1 .Lsc_top_p5
	s_mov_b64 exec, 0xffff
.Lsc_top_p5:
	s_nop 0
	global_load_lds_dwordx4 v0, s[16:17]
	s_mov_b64 exec, -1

.Lsu_w6:
	s_waitcnt vmcnt(4)
	s_cmpk_gt_i32 s0, 0x7fff
	v_cmp_gt_u32_e32 vcc, 4, v54
	s_cbranch_scc0 .Lsu_rw_fin
	s_add_i32 s2, s0, 0xffff8000
	s_bfe_u32 s1, s2, 0x30005
	s_lshr_b32 s2, s2, 6
	s_and_b32 s4, s2, 0x1fffffc
	s_add_i32 s2, s4, 0x2000
	v_pk_mul_f32 v[160:161], v[52:53], v[62:63]
	v_pk_mul_f32 v[168:169], v[46:47], v[60:61]
	v_pk_fma_f32 v[160:161], v[50:51], v[58:59], v[160:161]
	v_pk_fma_f32 v[168:169], v[48:49], v[56:57], v[168:169]
	s_nop 0
	v_pk_add_f32 v[160:161], v[168:169], v[160:161]
	s_nop 0
	v_add_f32_e32 v45, v160, v161
	s_nop 1
	v_add_f32_dpp v45, v45, v45 quad_perm:[1,0,3,2] row_mask:0xf bank_mask:0xf bound_ctrl:1
	s_nop 1
	v_add_f32_dpp v45, v45, v45 quad_perm:[2,3,0,1] row_mask:0xf bank_mask:0xf bound_ctrl:1
	s_nop 1
	v_add_f32_dpp v45, v45, v45 row_half_mirror row_mask:0xf bank_mask:0xf bound_ctrl:1
	s_nop 1
	v_add_f32_dpp v45, v45, v45 row_ror:8 row_mask:0xf bank_mask:0xf bound_ctrl:1
	s_nop 0
	v_fma_f32 v0, -v163, v45, v220
	v_mul_f32_e32 v0, v162, v0
	v_pk_mul_f32 v[60:61], v[60:61], v[0:1] op_sel_hi:[1,0]
	v_pk_mul_f32 v[62:63], v[62:63], v[0:1] op_sel_hi:[1,0]
	v_pk_fma_f32 v[46:47], v[46:47], v[162:163], v[60:61] op_sel:[0,1,0]
	v_pk_fma_f32 v[52:53], v[52:53], v[162:163], v[62:63] op_sel:[0,1,0]
	v_pk_mul_f32 v[58:59], v[58:59], v[0:1] op_sel_hi:[1,0]
	v_pk_mul_f32 v[56:57], v[56:57], v[0:1] op_sel_hi:[1,0]
	v_pk_fma_f32 v[50:51], v[50:51], v[162:163], v[58:59] op_sel:[0,1,0]
	v_pk_fma_f32 v[48:49], v[48:49], v[162:163], v[56:57] op_sel:[0,1,0]
	v_pk_mul_f32 v[56:57], v[68:69], v[46:47]
	v_pk_mul_f32 v[58:59], v[70:71], v[52:53]
	v_pk_fma_f32 v[56:57], v[48:49], v[64:65], v[56:57]
	v_pk_fma_f32 v[58:59], v[50:51], v[66:67], v[58:59]
	s_nop 0
	v_pk_add_f32 v[56:57], v[56:57], v[58:59]
	s_nop 0
	v_pk_mul_f32 v[58:59], v[78:79], v[52:53]
	v_add_f32_e32 v0, v56, v57
	v_pk_mul_f32 v[56:57], v[76:77], v[46:47]
	v_pk_fma_f32 v[58:59], v[50:51], v[74:75], v[58:59]
	v_pk_fma_f32 v[56:57], v[48:49], v[72:73], v[56:57]
	v_add_f32_dpp v0, v0, v0 quad_perm:[1,0,3,2] row_mask:0xf bank_mask:0xf bound_ctrl:1
	v_pk_add_f32 v[56:57], v[56:57], v[58:59]
	s_nop 0
	v_add_f32_e32 v56, v56, v57
	v_add_f32_dpp v0, v0, v0 quad_perm:[2,3,0,1] row_mask:0xf bank_mask:0xf bound_ctrl:1
	s_nop 0
	v_add_f32_dpp v56, v56, v56 quad_perm:[1,0,3,2] row_mask:0xf bank_mask:0xf bound_ctrl:1
	v_add_f32_dpp v0, v0, v0 row_half_mirror row_mask:0xf bank_mask:0xf bound_ctrl:1
	s_nop 0
	v_add_f32_dpp v56, v56, v56 quad_perm:[2,3,0,1] row_mask:0xf bank_mask:0xf bound_ctrl:1
	v_mov_b32_dpp v45, v0 row_ror:8 row_mask:0xf bank_mask:0xf bound_ctrl:1
	s_nop 0
	v_add_f32_dpp v56, v56, v56 row_half_mirror row_mask:0xf bank_mask:0xf bound_ctrl:1
	s_nop 1
	v_add_f32_dpp v56, v56, v56 row_ror:8 row_mask:0xf bank_mask:0xf bound_ctrl:1
	s_nop 0
	v_fma_f32 v55, -v165, v56, v55
	v_mul_f32_e32 v56, v164, v55
	v_pk_mul_f32 v[58:59], v[76:77], v[56:57] op_sel_hi:[1,0]
	v_pk_mul_f32 v[60:61], v[78:79], v[56:57] op_sel_hi:[1,0]
	v_pk_fma_f32 v[46:47], v[164:165], v[46:47], v[58:59] op_sel:[1,0,0]
	v_pk_fma_f32 v[52:53], v[164:165], v[52:53], v[60:61] op_sel:[1,0,0]
	v_pk_mul_f32 v[58:59], v[74:75], v[56:57] op_sel_hi:[1,0]
	v_pk_mul_f32 v[56:57], v[72:73], v[56:57] op_sel_hi:[1,0]
	v_pk_fma_f32 v[50:51], v[164:165], v[50:51], v[58:59] op_sel:[1,0,0]
	v_pk_fma_f32 v[48:49], v[164:165], v[48:49], v[56:57] op_sel:[1,0,0]
	v_pk_mul_f32 v[56:57], v[84:85], v[46:47]
	v_pk_mul_f32 v[58:59], v[86:87], v[52:53]
	v_pk_fma_f32 v[56:57], v[48:49], v[80:81], v[56:57]
	v_pk_fma_f32 v[58:59], v[50:51], v[82:83], v[58:59]
	s_nop 0
	v_pk_mul_f32 v[60:61], v[94:95], v[52:53]
	v_pk_add_f32 v[56:57], v[56:57], v[58:59]
	v_pk_mul_f32 v[58:59], v[92:93], v[46:47]
	v_pk_fma_f32 v[60:61], v[50:51], v[90:91], v[60:61]
	v_pk_fma_f32 v[58:59], v[48:49], v[88:89], v[58:59]
	v_add_f32_e32 v55, v56, v57
	v_pk_add_f32 v[58:59], v[58:59], v[60:61]
	s_nop 0
	v_add_f32_e32 v57, v58, v59
	v_add_f32_dpp v55, v55, v55 quad_perm:[1,0,3,2] row_mask:0xf bank_mask:0xf bound_ctrl:1
	s_nop 0
	v_add_f32_dpp v57, v57, v57 quad_perm:[1,0,3,2] row_mask:0xf bank_mask:0xf bound_ctrl:1
	v_add_f32_dpp v55, v55, v55 quad_perm:[2,3,0,1] row_mask:0xf bank_mask:0xf bound_ctrl:1
	s_nop 0
	v_add_f32_dpp v57, v57, v57 quad_perm:[2,3,0,1] row_mask:0xf bank_mask:0xf bound_ctrl:1
	v_add_f32_dpp v55, v55, v55 row_half_mirror row_mask:0xf bank_mask:0xf bound_ctrl:1
	s_nop 0
	v_add_f32_dpp v57, v57, v57 row_half_mirror row_mask:0xf bank_mask:0xf bound_ctrl:1
	v_mov_b32_dpp v56, v55 row_ror:8 row_mask:0xf bank_mask:0xf bound_ctrl:1
	s_nop 0
	v_add_f32_dpp v57, v57, v57 row_ror:8 row_mask:0xf bank_mask:0xf bound_ctrl:1
	s_nop 0
	v_fma_f32 v57, -v167, v57, v170
	v_mul_f32_e32 v58, v166, v57
	v_pk_mul_f32 v[60:61], v[92:93], v[58:59] op_sel_hi:[1,0]
	v_pk_mul_f32 v[62:63], v[94:95], v[58:59] op_sel_hi:[1,0]
	v_pk_fma_f32 v[60:61], v[166:167], v[46:47], v[60:61] op_sel:[1,0,0]
	v_pk_fma_f32 v[52:53], v[166:167], v[52:53], v[62:63] op_sel:[1,0,0]
	v_pk_mul_f32 v[46:47], v[90:91], v[58:59] op_sel_hi:[1,0]
	v_pk_mul_f32 v[58:59], v[88:89], v[58:59] op_sel_hi:[1,0]
	s_nop 0
	v_pk_fma_f32 v[62:63], v[166:167], v[48:49], v[58:59] op_sel:[1,0,0]
	v_pk_fma_f32 v[48:49], v[166:167], v[50:51], v[46:47] op_sel:[1,0,0]
	v_pk_mul_f32 v[46:47], v[100:101], v[60:61]
	v_pk_mul_f32 v[50:51], v[102:103], v[52:53]
	v_pk_fma_f32 v[46:47], v[62:63], v[96:97], v[46:47]
	v_pk_fma_f32 v[50:51], v[48:49], v[98:99], v[50:51]
	s_nop 0
	v_pk_add_f32 v[46:47], v[46:47], v[50:51]
	s_nop 0
	v_pk_mul_f32 v[50:51], v[150:151], v[52:53]
	v_add_f32_e32 v46, v46, v47
	v_pk_fma_f32 v[50:51], v[48:49], v[118:119], v[50:51]
	s_nop 0
	v_add_f32_dpp v46, v46, v46 quad_perm:[1,0,3,2] row_mask:0xf bank_mask:0xf bound_ctrl:1
	s_nop 1
	v_add_f32_dpp v46, v46, v46 quad_perm:[2,3,0,1] row_mask:0xf bank_mask:0xf bound_ctrl:1
	s_nop 1
	v_add_f32_dpp v57, v46, v46 row_half_mirror row_mask:0xf bank_mask:0xf bound_ctrl:1
	v_pk_mul_f32 v[46:47], v[148:149], v[60:61]
	s_nop 0
	v_pk_fma_f32 v[46:47], v[62:63], v[116:117], v[46:47]
	v_mov_b32_dpp v58, v57 row_ror:8 row_mask:0xf bank_mask:0xf bound_ctrl:1
	v_pk_add_f32 v[46:47], v[46:47], v[50:51]
	s_nop 0
	v_add_f32_e32 v46, v46, v47
	s_nop 1
	v_add_f32_dpp v46, v46, v46 quad_perm:[1,0,3,2] row_mask:0xf bank_mask:0xf bound_ctrl:1
	s_nop 1
	v_add_f32_dpp v46, v46, v46 quad_perm:[2,3,0,1] row_mask:0xf bank_mask:0xf bound_ctrl:1
	s_nop 1
	v_add_f32_dpp v46, v46, v46 row_half_mirror row_mask:0xf bank_mask:0xf bound_ctrl:1
	s_nop 1
	v_add_f32_dpp v46, v46, v46 row_ror:8 row_mask:0xf bank_mask:0xf bound_ctrl:1
	s_nop 0
	v_fma_f32 v46, -v105, v46, v171
	v_mul_f32_e32 v64, v104, v46
	v_pk_mul_f32 v[50:51], v[148:149], v[64:65] op_sel_hi:[1,0]
	v_pk_mul_f32 v[46:47], v[150:151], v[64:65] op_sel_hi:[1,0]
	v_pk_fma_f32 v[50:51], v[104:105], v[60:61], v[50:51] op_sel:[1,0,0]
	v_pk_fma_f32 v[46:47], v[104:105], v[52:53], v[46:47] op_sel:[1,0,0]
	v_pk_mul_f32 v[52:53], v[116:117], v[64:65] op_sel_hi:[1,0]
	v_pk_mul_f32 v[60:61], v[118:119], v[64:65] op_sel_hi:[1,0]
	v_pk_fma_f32 v[52:53], v[104:105], v[62:63], v[52:53] op_sel:[1,0,0]
	v_pk_fma_f32 v[48:49], v[104:105], v[48:49], v[60:61] op_sel:[1,0,0]
	v_pk_mul_f32 v[60:61], v[156:157], v[50:51]
	v_pk_mul_f32 v[62:63], v[158:159], v[46:47]
	v_pk_fma_f32 v[60:61], v[52:53], v[152:153], v[60:61]
	v_pk_fma_f32 v[62:63], v[48:49], v[154:155], v[62:63]
	s_nop 0
	v_pk_add_f32 v[60:61], v[60:61], v[62:63]
	s_nop 0
	v_add_f32_e32 v59, v60, v61
	s_nop 1
	v_add_f32_dpp v59, v59, v59 quad_perm:[1,0,3,2] row_mask:0xf bank_mask:0xf bound_ctrl:1
	s_nop 1
	v_add_f32_dpp v59, v59, v59 quad_perm:[2,3,0,1] row_mask:0xf bank_mask:0xf bound_ctrl:1
	s_nop 1
	v_add_f32_dpp v59, v59, v59 row_half_mirror row_mask:0xf bank_mask:0xf bound_ctrl:1
	s_nop 1
	v_mov_b32_dpp v60, v59 row_ror:8 row_mask:0xf bank_mask:0xf bound_ctrl:1
	s_and_saveexec_b64 s[24:25], vcc
	s_cbranch_execz .Lsu_gd_st
	v_add_f32_e32 v0, v0, v45
	v_cmp_eq_u32_e32 vcc, 0, v54
	s_lshl_b32 s1, s1, 7
	v_or_b32_e32 v62, s2, v54
	v_mov_b32_e32 v63, v1
	v_readlane_b32 s2, v251, 47
	v_add_f32_e32 v55, v55, v56
	v_cndmask_b32_e32 v0, 0, v0, vcc
	v_cmp_eq_u32_e32 vcc, 1, v54
	v_lshlrev_b64 v[62:63], 12, v[62:63]
	v_readlane_b32 s3, v251, 48
	v_add_u32_e32 v64, s1, v44
	v_add_f32_e32 v57, v57, v58
	v_cndmask_b32_e32 v0, v0, v55, vcc
	v_cmp_eq_u32_e32 vcc, 2, v54
	v_lshl_add_u64 v[62:63], s[2:3], 0, v[62:63]
	v_ashrrev_i32_e32 v65, 31, v64
	v_add_f32_e32 v44, v59, v60
	v_cndmask_b32_e32 v0, v0, v57, vcc
	v_cmp_eq_u32_e32 vcc, 3, v54
	v_lshl_add_u64 v[62:63], v[64:65], 2, v[62:63]
	s_nop 0
	v_cndmask_b32_e32 v0, v0, v44, vcc
	global_store_dword v[62:63], v0, off

.Lstga_1242:
	s_waitcnt vmcnt(9)
	s_branch .LBB0_1789

.Lstgb_1242:
	s_waitcnt vmcnt(2)
	s_branch .LBB0_1789

.Lstgc_1242:
	s_waitcnt vmcnt(32)
	s_branch .LBB0_1789

.Lstgd_1242:
	s_waitcnt vmcnt(25)
	s_branch .LBB0_1789
